# scan blocks run at wave priority 0 (equal to the attention CU-mate) instead of 3
# baseline (speedup 1.0000x reference)
.LBB0_450:
	s_setprio 0
	v_mov_b32_e32 v86, v175
	s_movk_i32 s0, 0x1ff
	s_nop 0
	v_cmp_lt_i32_e32 vcc, s0, v86
	s_waitcnt vmcnt(6)
	v_lshlrev_b32_e32 v27, 4, v86
	s_barrier
	s_and_saveexec_b64 s[0:1], vcc
	s_xor_b64 s[4:5], exec, s[0:1]
	v_lshlrev_b32_e32 v26, 4, v86
	s_andn2_saveexec_b64 s[4:5], s[4:5]
	s_cbranch_execz .LBB0_456
	v_readlane_b32 s0, v255, 11
	v_add_u32_e32 v2, 0xffffff00, v86
	s_mov_b64 s[6:7], 0
	v_add_u32_e32 v0, s0, v27
